# rwkv_post software pipelined: per-channel parameters hoisted, next row's five operands requested before the current row is computed, DPP 8-lane sums
# speedup vs baseline: 1.0973x; 1.0062x over previous
.LBB0_1451:
	s_or_b64 exec, exec, s[4:5]
	s_mov_b64 s[10:11], s[0:1]
	s_mov_b32 s18, s2
	s_waitcnt vmcnt(7) lgkmcnt(0)
	v_mov_b32_e32 v0, v154
	s_barrier
	s_load_dwordx2 s[6:7], s[0:1], 0x138
	s_load_dwordx2 s[16:17], s[0:1], 0x88
	s_load_dwordx2 s[8:9], s[0:1], 0xd0
	v_lshrrev_b32_e32 v80, 6, v154
	v_lshl_add_u32 v80, s2, 3, v80
	v_bfe_u32 v81, v154, 3, 3
	v_and_b32_e32 v82, 7, v154
	v_lshlrev_b32_e32 v83, 6, v81
	v_lshl_add_u32 v83, v82, 3, v83
	v_lshrrev_b32_e32 v84, 1, v82
	v_lshl_add_u32 v84, v81, 2, v84
	v_lshl_add_u32 v84, v84, 11, v80
	v_and_b32_e32 v85, 1, v82
	v_lshlrev_b32_e32 v85, 4, v85
	v_lshl_add_u32 v60, v84, 5, v85
	v_mul_u32_u24_e32 v61, 0x1e00, v80
	v_lshl_add_u32 v61, v83, 1, v61
	v_mul_u32_u24_e32 v62, 0xc00, v80
	v_lshl_add_u32 v62, v83, 1, v62
	v_lshlrev_b32_e32 v63, 13, v81
	v_lshl_add_u32 v63, v80, 2, v63
	v_lshlrev_b32_e32 v86, 2, v83
	v_cmp_ne_u32_e64 s[26:27], 0, v80
	v_mov_b32_e32 v87, 0x3a27c5ac
	s_waitcnt lgkmcnt(0)
	s_add_u32 s16, s16, 0x1000
	s_addc_u32 s17, s17, 0
	global_load_dwordx4 v[64:67], v86, s[16:17]
	global_load_dwordx4 v[68:71], v86, s[16:17] offset:16
	global_load_dwordx4 v[72:75], v86, s[8:9]
	global_load_dwordx4 v[76:79], v86, s[8:9] offset:16
	v_add_u32_e32 v88, 0x1000, v61
	v_add_u32_e32 v89, 0, v61
	s_add_u32 s10, s6, 0x3300000
	s_addc_u32 s11, s7, 0
	s_add_u32 s12, s6, 0x4300000
	s_addc_u32 s13, s7, 0
	s_add_u32 s14, s6, 0xbb00000
	s_addc_u32 s15, s7, 0
	s_add_u32 s18, s6, 0xfb00000
	s_addc_u32 s19, s7, 0
	global_load_dwordx4 v[0:3], v60, s[10:11]
	global_load_dwordx4 v[4:7], v88, s[12:13] offset:2048
	global_load_dwordx4 v[8:11], v89, s[12:13] offset:-1536
	global_load_dwordx4 v[12:15], v62, s[14:15] offset:2048
	global_load_dword v16, v63, s[18:19]
	s_add_u32 s10, s6, 0x3500000
	s_addc_u32 s11, s7, 0
	s_add_u32 s12, s6, 0x5200000
	s_addc_u32 s13, s7, 0
	s_add_u32 s14, s6, 0xc100000
	s_addc_u32 s15, s7, 0
	s_add_u32 s18, s6, 0xfb10000
	s_addc_u32 s19, s7, 0
	global_load_dwordx4 v[20:23], v60, s[10:11]
	global_load_dwordx4 v[24:27], v88, s[12:13] offset:2048
	global_load_dwordx4 v[28:31], v89, s[12:13] offset:-1536
	global_load_dwordx4 v[32:35], v62, s[14:15] offset:2048
	global_load_dword v36, v63, s[18:19]
	s_waitcnt vmcnt(5)
	v_lshlrev_b32_e32 v40, 16, v0
	v_and_b32_e32 v41, 0xffff0000, v0
	v_lshlrev_b32_e32 v42, 16, v1
	v_and_b32_e32 v43, 0xffff0000, v1
	v_lshlrev_b32_e32 v44, 16, v2
	v_and_b32_e32 v45, 0xffff0000, v2
	v_lshlrev_b32_e32 v46, 16, v3
	v_and_b32_e32 v47, 0xffff0000, v3
	v_add_f32_e32 v56, 0, v40
	v_add_f32_e32 v56, v56, v41
	v_add_f32_e32 v56, v56, v42
	v_add_f32_e32 v56, v56, v43
	v_add_f32_e32 v56, v56, v44
	v_add_f32_e32 v56, v56, v45
	v_add_f32_e32 v56, v56, v46
	v_add_f32_e32 v56, v56, v47
	s_nop 1
	v_add_f32_dpp v56, v56, v56 quad_perm:[1,0,3,2] row_mask:0xf bank_mask:0xf
	s_nop 1
	v_add_f32_dpp v56, v56, v56 quad_perm:[2,3,0,1] row_mask:0xf bank_mask:0xf
	s_nop 1
	v_add_f32_dpp v56, v56, v56 row_half_mirror row_mask:0xf bank_mask:0xf
	v_mul_f32_e32 v57, 0x3c800000, v56
	v_sub_f32_e32 v40, v40, v57
	v_sub_f32_e32 v41, v41, v57
	v_sub_f32_e32 v42, v42, v57
	v_sub_f32_e32 v43, v43, v57
	v_sub_f32_e32 v44, v44, v57
	v_sub_f32_e32 v45, v45, v57
	v_sub_f32_e32 v46, v46, v57
	v_sub_f32_e32 v47, v47, v57
	v_mul_f32_e32 v56, v40, v40
	v_mul_f32_e32 v58, v41, v41
	v_add_f32_e32 v56, v56, v58
	v_mul_f32_e32 v58, v42, v42
	v_add_f32_e32 v56, v58, v56
	v_mul_f32_e32 v58, v43, v43
	v_add_f32_e32 v56, v58, v56
	v_mul_f32_e32 v58, v44, v44
	v_add_f32_e32 v56, v58, v56
	v_mul_f32_e32 v58, v45, v45
	v_add_f32_e32 v56, v58, v56
	v_mul_f32_e32 v58, v46, v46
	v_add_f32_e32 v56, v58, v56
	v_mul_f32_e32 v58, v47, v47
	v_add_f32_e32 v56, v58, v56
	s_nop 1
	v_add_f32_dpp v56, v56, v56 quad_perm:[1,0,3,2] row_mask:0xf bank_mask:0xf
	s_nop 1
	v_add_f32_dpp v56, v56, v56 quad_perm:[2,3,0,1] row_mask:0xf bank_mask:0xf
	s_nop 1
	v_add_f32_dpp v56, v56, v56 row_half_mirror row_mask:0xf bank_mask:0xf
	v_fmamk_f32 v56, v56, 0x3c800000, v87
	v_rsq_f32_e32 v56, v56
	v_cndmask_b32_e64 v8, 0, v8, s[26:27]
	v_cndmask_b32_e64 v9, 0, v9, s[26:27]
	v_cndmask_b32_e64 v10, 0, v10, s[26:27]
	v_cndmask_b32_e64 v11, 0, v11, s[26:27]
	v_lshlrev_b32_e32 v90, 16, v4
	v_and_b32_e32 v91, 0xffff0000, v4
	v_lshlrev_b32_e32 v48, 16, v8
	v_and_b32_e32 v49, 0xffff0000, v8
	v_lshlrev_b32_e32 v92, 16, v5
	v_and_b32_e32 v93, 0xffff0000, v5
	v_lshlrev_b32_e32 v50, 16, v9
	v_and_b32_e32 v51, 0xffff0000, v9
	v_lshlrev_b32_e32 v94, 16, v6
	v_and_b32_e32 v95, 0xffff0000, v6
	v_lshlrev_b32_e32 v52, 16, v10
	v_and_b32_e32 v53, 0xffff0000, v10
	v_lshlrev_b32_e32 v96, 16, v7
	v_and_b32_e32 v97, 0xffff0000, v7
	v_lshlrev_b32_e32 v54, 16, v11
	v_and_b32_e32 v55, 0xffff0000, v11
	v_sub_f32_e32 v48, v48, v90
	v_sub_f32_e32 v49, v49, v91
	v_sub_f32_e32 v50, v50, v92
	v_sub_f32_e32 v51, v51, v93
	v_sub_f32_e32 v52, v52, v94
	v_sub_f32_e32 v53, v53, v95
	v_sub_f32_e32 v54, v54, v96
	v_sub_f32_e32 v55, v55, v97
	v_mul_f32_e32 v40, v40, v56
	v_mul_f32_e32 v41, v41, v56
	v_mul_f32_e32 v42, v42, v56
	v_mul_f32_e32 v43, v43, v56
	v_mul_f32_e32 v44, v44, v56
	v_mul_f32_e32 v45, v45, v56
	v_mul_f32_e32 v46, v46, v56
	v_mul_f32_e32 v47, v47, v56
	v_fma_f32 v90, v48, v64, v90
	v_fma_f32 v91, v49, v65, v91
	v_fma_f32 v92, v50, v66, v92
	v_fma_f32 v93, v51, v67, v93
	v_fma_f32 v94, v52, v68, v94
	v_fma_f32 v95, v53, v69, v95
	v_fma_f32 v96, v54, v70, v96
	v_fma_f32 v97, v55, v71, v97
	v_mul_f32_e32 v90, v16, v90
	v_mul_f32_e32 v91, v16, v91
	v_mul_f32_e32 v92, v16, v92
	v_mul_f32_e32 v93, v16, v93
	v_mul_f32_e32 v94, v16, v94
	v_mul_f32_e32 v95, v16, v95
	v_mul_f32_e32 v96, v16, v96
	v_mul_f32_e32 v97, v16, v97
	v_fma_f32 v90, v40, v72, v90
	v_fma_f32 v91, v41, v73, v91
	v_fma_f32 v92, v42, v74, v92
	v_fma_f32 v93, v43, v75, v93
	v_fma_f32 v94, v44, v76, v94
	v_fma_f32 v95, v45, v77, v95
	v_fma_f32 v96, v46, v78, v96
	v_fma_f32 v97, v47, v79, v97
	v_lshlrev_b32_e32 v48, 16, v12
	v_and_b32_e32 v49, 0xffff0000, v12
	v_lshlrev_b32_e32 v50, 16, v13
	v_and_b32_e32 v51, 0xffff0000, v13
	v_lshlrev_b32_e32 v52, 16, v14
	v_and_b32_e32 v53, 0xffff0000, v14
	v_lshlrev_b32_e32 v54, 16, v15
	v_and_b32_e32 v55, 0xffff0000, v15
	v_mul_f32_e32 v90, v90, v48
	v_mul_f32_e32 v91, v91, v49
	v_mul_f32_e32 v92, v92, v50
	v_mul_f32_e32 v93, v93, v51
	v_mul_f32_e32 v94, v94, v52
	v_mul_f32_e32 v95, v95, v53
	v_mul_f32_e32 v96, v96, v54
	v_mul_f32_e32 v97, v97, v55
	v_cvt_pk_bf16_f32 v98, v90, v91
	v_cvt_pk_bf16_f32 v99, v92, v93
	v_cvt_pk_bf16_f32 v100, v94, v95
	v_cvt_pk_bf16_f32 v101, v96, v97
	s_add_u32 s28, s6, 0x4300000
	s_addc_u32 s29, s7, 0
	global_store_dwordx4 v61, v[98:101], s[28:29] offset:1024
	s_add_u32 s10, s6, 0x3700000
	s_addc_u32 s11, s7, 0
	s_add_u32 s12, s6, 0x6100000
	s_addc_u32 s13, s7, 0
	s_add_u32 s14, s6, 0xc700000
	s_addc_u32 s15, s7, 0
	s_add_u32 s18, s6, 0xfb20000
	s_addc_u32 s19, s7, 0
	global_load_dwordx4 v[0:3], v60, s[10:11]
	global_load_dwordx4 v[4:7], v88, s[12:13] offset:2048
	global_load_dwordx4 v[8:11], v89, s[12:13] offset:-1536
	global_load_dwordx4 v[12:15], v62, s[14:15] offset:2048
	global_load_dword v16, v63, s[18:19]
	s_waitcnt vmcnt(5)
	v_lshlrev_b32_e32 v40, 16, v20
	v_and_b32_e32 v41, 0xffff0000, v20
	v_lshlrev_b32_e32 v42, 16, v21
	v_and_b32_e32 v43, 0xffff0000, v21
	v_lshlrev_b32_e32 v44, 16, v22
	v_and_b32_e32 v45, 0xffff0000, v22
	v_lshlrev_b32_e32 v46, 16, v23
	v_and_b32_e32 v47, 0xffff0000, v23
	v_add_f32_e32 v56, 0, v40
	v_add_f32_e32 v56, v56, v41
	v_add_f32_e32 v56, v56, v42
	v_add_f32_e32 v56, v56, v43
	v_add_f32_e32 v56, v56, v44
	v_add_f32_e32 v56, v56, v45
	v_add_f32_e32 v56, v56, v46
	v_add_f32_e32 v56, v56, v47
	s_nop 1
	v_add_f32_dpp v56, v56, v56 quad_perm:[1,0,3,2] row_mask:0xf bank_mask:0xf
	s_nop 1
	v_add_f32_dpp v56, v56, v56 quad_perm:[2,3,0,1] row_mask:0xf bank_mask:0xf
	s_nop 1
	v_add_f32_dpp v56, v56, v56 row_half_mirror row_mask:0xf bank_mask:0xf
	v_mul_f32_e32 v57, 0x3c800000, v56
	v_sub_f32_e32 v40, v40, v57
	v_sub_f32_e32 v41, v41, v57
	v_sub_f32_e32 v42, v42, v57
	v_sub_f32_e32 v43, v43, v57
	v_sub_f32_e32 v44, v44, v57
	v_sub_f32_e32 v45, v45, v57
	v_sub_f32_e32 v46, v46, v57
	v_sub_f32_e32 v47, v47, v57
	v_mul_f32_e32 v56, v40, v40
	v_mul_f32_e32 v58, v41, v41
	v_add_f32_e32 v56, v56, v58
	v_mul_f32_e32 v58, v42, v42
	v_add_f32_e32 v56, v58, v56
	v_mul_f32_e32 v58, v43, v43
	v_add_f32_e32 v56, v58, v56
	v_mul_f32_e32 v58, v44, v44
	v_add_f32_e32 v56, v58, v56
	v_mul_f32_e32 v58, v45, v45
	v_add_f32_e32 v56, v58, v56
	v_mul_f32_e32 v58, v46, v46
	v_add_f32_e32 v56, v58, v56
	v_mul_f32_e32 v58, v47, v47
	v_add_f32_e32 v56, v58, v56
	s_nop 1
	v_add_f32_dpp v56, v56, v56 quad_perm:[1,0,3,2] row_mask:0xf bank_mask:0xf
	s_nop 1
	v_add_f32_dpp v56, v56, v56 quad_perm:[2,3,0,1] row_mask:0xf bank_mask:0xf
	s_nop 1
	v_add_f32_dpp v56, v56, v56 row_half_mirror row_mask:0xf bank_mask:0xf
	v_fmamk_f32 v56, v56, 0x3c800000, v87
	v_rsq_f32_e32 v56, v56
	v_cndmask_b32_e64 v28, 0, v28, s[26:27]
	v_cndmask_b32_e64 v29, 0, v29, s[26:27]
	v_cndmask_b32_e64 v30, 0, v30, s[26:27]
	v_cndmask_b32_e64 v31, 0, v31, s[26:27]
	v_lshlrev_b32_e32 v90, 16, v24
	v_and_b32_e32 v91, 0xffff0000, v24
	v_lshlrev_b32_e32 v48, 16, v28
	v_and_b32_e32 v49, 0xffff0000, v28
	v_lshlrev_b32_e32 v92, 16, v25
	v_and_b32_e32 v93, 0xffff0000, v25
	v_lshlrev_b32_e32 v50, 16, v29
	v_and_b32_e32 v51, 0xffff0000, v29
	v_lshlrev_b32_e32 v94, 16, v26
	v_and_b32_e32 v95, 0xffff0000, v26
	v_lshlrev_b32_e32 v52, 16, v30
	v_and_b32_e32 v53, 0xffff0000, v30
	v_lshlrev_b32_e32 v96, 16, v27
	v_and_b32_e32 v97, 0xffff0000, v27
	v_lshlrev_b32_e32 v54, 16, v31
	v_and_b32_e32 v55, 0xffff0000, v31
	v_sub_f32_e32 v48, v48, v90
	v_sub_f32_e32 v49, v49, v91
	v_sub_f32_e32 v50, v50, v92
	v_sub_f32_e32 v51, v51, v93
	v_sub_f32_e32 v52, v52, v94
	v_sub_f32_e32 v53, v53, v95
	v_sub_f32_e32 v54, v54, v96
	v_sub_f32_e32 v55, v55, v97
	v_mul_f32_e32 v40, v40, v56
	v_mul_f32_e32 v41, v41, v56
	v_mul_f32_e32 v42, v42, v56
	v_mul_f32_e32 v43, v43, v56
	v_mul_f32_e32 v44, v44, v56
	v_mul_f32_e32 v45, v45, v56
	v_mul_f32_e32 v46, v46, v56
	v_mul_f32_e32 v47, v47, v56
	v_fma_f32 v90, v48, v64, v90
	v_fma_f32 v91, v49, v65, v91
	v_fma_f32 v92, v50, v66, v92
	v_fma_f32 v93, v51, v67, v93
	v_fma_f32 v94, v52, v68, v94
	v_fma_f32 v95, v53, v69, v95
	v_fma_f32 v96, v54, v70, v96
	v_fma_f32 v97, v55, v71, v97
	v_mul_f32_e32 v90, v36, v90
	v_mul_f32_e32 v91, v36, v91
	v_mul_f32_e32 v92, v36, v92
	v_mul_f32_e32 v93, v36, v93
	v_mul_f32_e32 v94, v36, v94
	v_mul_f32_e32 v95, v36, v95
	v_mul_f32_e32 v96, v36, v96
	v_mul_f32_e32 v97, v36, v97
	v_fma_f32 v90, v40, v72, v90
	v_fma_f32 v91, v41, v73, v91
	v_fma_f32 v92, v42, v74, v92
	v_fma_f32 v93, v43, v75, v93
	v_fma_f32 v94, v44, v76, v94
	v_fma_f32 v95, v45, v77, v95
	v_fma_f32 v96, v46, v78, v96
	v_fma_f32 v97, v47, v79, v97
	v_lshlrev_b32_e32 v48, 16, v32
	v_and_b32_e32 v49, 0xffff0000, v32
	v_lshlrev_b32_e32 v50, 16, v33
	v_and_b32_e32 v51, 0xffff0000, v33
	v_lshlrev_b32_e32 v52, 16, v34
	v_and_b32_e32 v53, 0xffff0000, v34
	v_lshlrev_b32_e32 v54, 16, v35
	v_and_b32_e32 v55, 0xffff0000, v35
	v_mul_f32_e32 v90, v90, v48
	v_mul_f32_e32 v91, v91, v49
	v_mul_f32_e32 v92, v92, v50
	v_mul_f32_e32 v93, v93, v51
	v_mul_f32_e32 v94, v94, v52
	v_mul_f32_e32 v95, v95, v53
	v_mul_f32_e32 v96, v96, v54
	v_mul_f32_e32 v97, v97, v55
	v_cvt_pk_bf16_f32 v102, v90, v91
	v_cvt_pk_bf16_f32 v103, v92, v93
	v_cvt_pk_bf16_f32 v104, v94, v95
	v_cvt_pk_bf16_f32 v105, v96, v97
	s_add_u32 s28, s6, 0x5200000
	s_addc_u32 s29, s7, 0
	global_store_dwordx4 v61, v[102:105], s[28:29] offset:1024
	s_add_u32 s10, s6, 0x3900000
	s_addc_u32 s11, s7, 0
	s_add_u32 s12, s6, 0x7000000
	s_addc_u32 s13, s7, 0
	s_add_u32 s14, s6, 0xcd00000
	s_addc_u32 s15, s7, 0
	s_add_u32 s18, s6, 0xfb30000
	s_addc_u32 s19, s7, 0
	global_load_dwordx4 v[20:23], v60, s[10:11]
	global_load_dwordx4 v[24:27], v88, s[12:13] offset:2048
	global_load_dwordx4 v[28:31], v89, s[12:13] offset:-1536
	global_load_dwordx4 v[32:35], v62, s[14:15] offset:2048
	global_load_dword v36, v63, s[18:19]
	s_waitcnt vmcnt(5)
	v_lshlrev_b32_e32 v40, 16, v0
	v_and_b32_e32 v41, 0xffff0000, v0
	v_lshlrev_b32_e32 v42, 16, v1
	v_and_b32_e32 v43, 0xffff0000, v1
	v_lshlrev_b32_e32 v44, 16, v2
	v_and_b32_e32 v45, 0xffff0000, v2
	v_lshlrev_b32_e32 v46, 16, v3
	v_and_b32_e32 v47, 0xffff0000, v3
	v_add_f32_e32 v56, 0, v40
	v_add_f32_e32 v56, v56, v41
	v_add_f32_e32 v56, v56, v42
	v_add_f32_e32 v56, v56, v43
	v_add_f32_e32 v56, v56, v44
	v_add_f32_e32 v56, v56, v45
	v_add_f32_e32 v56, v56, v46
	v_add_f32_e32 v56, v56, v47
	s_nop 1
	v_add_f32_dpp v56, v56, v56 quad_perm:[1,0,3,2] row_mask:0xf bank_mask:0xf
	s_nop 1
	v_add_f32_dpp v56, v56, v56 quad_perm:[2,3,0,1] row_mask:0xf bank_mask:0xf
	s_nop 1
	v_add_f32_dpp v56, v56, v56 row_half_mirror row_mask:0xf bank_mask:0xf
	v_mul_f32_e32 v57, 0x3c800000, v56
	v_sub_f32_e32 v40, v40, v57
	v_sub_f32_e32 v41, v41, v57
	v_sub_f32_e32 v42, v42, v57
	v_sub_f32_e32 v43, v43, v57
	v_sub_f32_e32 v44, v44, v57
	v_sub_f32_e32 v45, v45, v57
	v_sub_f32_e32 v46, v46, v57
	v_sub_f32_e32 v47, v47, v57
	v_mul_f32_e32 v56, v40, v40
	v_mul_f32_e32 v58, v41, v41
	v_add_f32_e32 v56, v56, v58
	v_mul_f32_e32 v58, v42, v42
	v_add_f32_e32 v56, v58, v56
	v_mul_f32_e32 v58, v43, v43
	v_add_f32_e32 v56, v58, v56
	v_mul_f32_e32 v58, v44, v44
	v_add_f32_e32 v56, v58, v56
	v_mul_f32_e32 v58, v45, v45
	v_add_f32_e32 v56, v58, v56
	v_mul_f32_e32 v58, v46, v46
	v_add_f32_e32 v56, v58, v56
	v_mul_f32_e32 v58, v47, v47
	v_add_f32_e32 v56, v58, v56
	s_nop 1
	v_add_f32_dpp v56, v56, v56 quad_perm:[1,0,3,2] row_mask:0xf bank_mask:0xf
	s_nop 1
	v_add_f32_dpp v56, v56, v56 quad_perm:[2,3,0,1] row_mask:0xf bank_mask:0xf
	s_nop 1
	v_add_f32_dpp v56, v56, v56 row_half_mirror row_mask:0xf bank_mask:0xf
	v_fmamk_f32 v56, v56, 0x3c800000, v87
	v_rsq_f32_e32 v56, v56
	v_cndmask_b32_e64 v8, 0, v8, s[26:27]
	v_cndmask_b32_e64 v9, 0, v9, s[26:27]
	v_cndmask_b32_e64 v10, 0, v10, s[26:27]
	v_cndmask_b32_e64 v11, 0, v11, s[26:27]
	v_lshlrev_b32_e32 v90, 16, v4
	v_and_b32_e32 v91, 0xffff0000, v4
	v_lshlrev_b32_e32 v48, 16, v8
	v_and_b32_e32 v49, 0xffff0000, v8
	v_lshlrev_b32_e32 v92, 16, v5
	v_and_b32_e32 v93, 0xffff0000, v5
	v_lshlrev_b32_e32 v50, 16, v9
	v_and_b32_e32 v51, 0xffff0000, v9
	v_lshlrev_b32_e32 v94, 16, v6
	v_and_b32_e32 v95, 0xffff0000, v6
	v_lshlrev_b32_e32 v52, 16, v10
	v_and_b32_e32 v53, 0xffff0000, v10
	v_lshlrev_b32_e32 v96, 16, v7
	v_and_b32_e32 v97, 0xffff0000, v7
	v_lshlrev_b32_e32 v54, 16, v11
	v_and_b32_e32 v55, 0xffff0000, v11
	v_sub_f32_e32 v48, v48, v90
	v_sub_f32_e32 v49, v49, v91
	v_sub_f32_e32 v50, v50, v92
	v_sub_f32_e32 v51, v51, v93
	v_sub_f32_e32 v52, v52, v94
	v_sub_f32_e32 v53, v53, v95
	v_sub_f32_e32 v54, v54, v96
	v_sub_f32_e32 v55, v55, v97
	v_mul_f32_e32 v40, v40, v56
	v_mul_f32_e32 v41, v41, v56
	v_mul_f32_e32 v42, v42, v56
	v_mul_f32_e32 v43, v43, v56
	v_mul_f32_e32 v44, v44, v56
	v_mul_f32_e32 v45, v45, v56
	v_mul_f32_e32 v46, v46, v56
	v_mul_f32_e32 v47, v47, v56
	v_fma_f32 v90, v48, v64, v90
	v_fma_f32 v91, v49, v65, v91
	v_fma_f32 v92, v50, v66, v92
	v_fma_f32 v93, v51, v67, v93
	v_fma_f32 v94, v52, v68, v94
	v_fma_f32 v95, v53, v69, v95
	v_fma_f32 v96, v54, v70, v96
	v_fma_f32 v97, v55, v71, v97
	v_mul_f32_e32 v90, v16, v90
	v_mul_f32_e32 v91, v16, v91
	v_mul_f32_e32 v92, v16, v92
	v_mul_f32_e32 v93, v16, v93
	v_mul_f32_e32 v94, v16, v94
	v_mul_f32_e32 v95, v16, v95
	v_mul_f32_e32 v96, v16, v96
	v_mul_f32_e32 v97, v16, v97
	v_fma_f32 v90, v40, v72, v90
	v_fma_f32 v91, v41, v73, v91
	v_fma_f32 v92, v42, v74, v92
	v_fma_f32 v93, v43, v75, v93
	v_fma_f32 v94, v44, v76, v94
	v_fma_f32 v95, v45, v77, v95
	v_fma_f32 v96, v46, v78, v96
	v_fma_f32 v97, v47, v79, v97
	v_lshlrev_b32_e32 v48, 16, v12
	v_and_b32_e32 v49, 0xffff0000, v12
	v_lshlrev_b32_e32 v50, 16, v13
	v_and_b32_e32 v51, 0xffff0000, v13
	v_lshlrev_b32_e32 v52, 16, v14
	v_and_b32_e32 v53, 0xffff0000, v14
	v_lshlrev_b32_e32 v54, 16, v15
	v_and_b32_e32 v55, 0xffff0000, v15
	v_mul_f32_e32 v90, v90, v48
	v_mul_f32_e32 v91, v91, v49
	v_mul_f32_e32 v92, v92, v50
	v_mul_f32_e32 v93, v93, v51
	v_mul_f32_e32 v94, v94, v52
	v_mul_f32_e32 v95, v95, v53
	v_mul_f32_e32 v96, v96, v54
	v_mul_f32_e32 v97, v97, v55
	v_cvt_pk_bf16_f32 v98, v90, v91
	v_cvt_pk_bf16_f32 v99, v92, v93
	v_cvt_pk_bf16_f32 v100, v94, v95
	v_cvt_pk_bf16_f32 v101, v96, v97
	s_add_u32 s28, s6, 0x6100000
	s_addc_u32 s29, s7, 0
	global_store_dwordx4 v61, v[98:101], s[28:29] offset:1024
	s_add_u32 s10, s6, 0x3b00000
	s_addc_u32 s11, s7, 0
	s_add_u32 s12, s6, 0x7f00000
	s_addc_u32 s13, s7, 0
	s_add_u32 s14, s6, 0xd300000
	s_addc_u32 s15, s7, 0
	s_add_u32 s18, s6, 0xfb40000
	s_addc_u32 s19, s7, 0
	global_load_dwordx4 v[0:3], v60, s[10:11]
	global_load_dwordx4 v[4:7], v88, s[12:13] offset:2048
	global_load_dwordx4 v[8:11], v89, s[12:13] offset:-1536
	global_load_dwordx4 v[12:15], v62, s[14:15] offset:2048
	global_load_dword v16, v63, s[18:19]
	s_waitcnt vmcnt(5)
	v_lshlrev_b32_e32 v40, 16, v20
	v_and_b32_e32 v41, 0xffff0000, v20
	v_lshlrev_b32_e32 v42, 16, v21
	v_and_b32_e32 v43, 0xffff0000, v21
	v_lshlrev_b32_e32 v44, 16, v22
	v_and_b32_e32 v45, 0xffff0000, v22
	v_lshlrev_b32_e32 v46, 16, v23
	v_and_b32_e32 v47, 0xffff0000, v23
	v_add_f32_e32 v56, 0, v40
	v_add_f32_e32 v56, v56, v41
	v_add_f32_e32 v56, v56, v42
	v_add_f32_e32 v56, v56, v43
	v_add_f32_e32 v56, v56, v44
	v_add_f32_e32 v56, v56, v45
	v_add_f32_e32 v56, v56, v46
	v_add_f32_e32 v56, v56, v47
	s_nop 1
	v_add_f32_dpp v56, v56, v56 quad_perm:[1,0,3,2] row_mask:0xf bank_mask:0xf
	s_nop 1
	v_add_f32_dpp v56, v56, v56 quad_perm:[2,3,0,1] row_mask:0xf bank_mask:0xf
	s_nop 1
	v_add_f32_dpp v56, v56, v56 row_half_mirror row_mask:0xf bank_mask:0xf
	v_mul_f32_e32 v57, 0x3c800000, v56
	v_sub_f32_e32 v40, v40, v57
	v_sub_f32_e32 v41, v41, v57
	v_sub_f32_e32 v42, v42, v57
	v_sub_f32_e32 v43, v43, v57
	v_sub_f32_e32 v44, v44, v57
	v_sub_f32_e32 v45, v45, v57
	v_sub_f32_e32 v46, v46, v57
	v_sub_f32_e32 v47, v47, v57
	v_mul_f32_e32 v56, v40, v40
	v_mul_f32_e32 v58, v41, v41
	v_add_f32_e32 v56, v56, v58
	v_mul_f32_e32 v58, v42, v42
	v_add_f32_e32 v56, v58, v56
	v_mul_f32_e32 v58, v43, v43
	v_add_f32_e32 v56, v58, v56
	v_mul_f32_e32 v58, v44, v44
	v_add_f32_e32 v56, v58, v56
	v_mul_f32_e32 v58, v45, v45
	v_add_f32_e32 v56, v58, v56
	v_mul_f32_e32 v58, v46, v46
	v_add_f32_e32 v56, v58, v56
	v_mul_f32_e32 v58, v47, v47
	v_add_f32_e32 v56, v58, v56
	s_nop 1
	v_add_f32_dpp v56, v56, v56 quad_perm:[1,0,3,2] row_mask:0xf bank_mask:0xf
	s_nop 1
	v_add_f32_dpp v56, v56, v56 quad_perm:[2,3,0,1] row_mask:0xf bank_mask:0xf
	s_nop 1
	v_add_f32_dpp v56, v56, v56 row_half_mirror row_mask:0xf bank_mask:0xf
	v_fmamk_f32 v56, v56, 0x3c800000, v87
	v_rsq_f32_e32 v56, v56
	v_cndmask_b32_e64 v28, 0, v28, s[26:27]
	v_cndmask_b32_e64 v29, 0, v29, s[26:27]
	v_cndmask_b32_e64 v30, 0, v30, s[26:27]
	v_cndmask_b32_e64 v31, 0, v31, s[26:27]
	v_lshlrev_b32_e32 v90, 16, v24
	v_and_b32_e32 v91, 0xffff0000, v24
	v_lshlrev_b32_e32 v48, 16, v28
	v_and_b32_e32 v49, 0xffff0000, v28
	v_lshlrev_b32_e32 v92, 16, v25
	v_and_b32_e32 v93, 0xffff0000, v25
	v_lshlrev_b32_e32 v50, 16, v29
	v_and_b32_e32 v51, 0xffff0000, v29
	v_lshlrev_b32_e32 v94, 16, v26
	v_and_b32_e32 v95, 0xffff0000, v26
	v_lshlrev_b32_e32 v52, 16, v30
	v_and_b32_e32 v53, 0xffff0000, v30
	v_lshlrev_b32_e32 v96, 16, v27
	v_and_b32_e32 v97, 0xffff0000, v27
	v_lshlrev_b32_e32 v54, 16, v31
	v_and_b32_e32 v55, 0xffff0000, v31
	v_sub_f32_e32 v48, v48, v90
	v_sub_f32_e32 v49, v49, v91
	v_sub_f32_e32 v50, v50, v92
	v_sub_f32_e32 v51, v51, v93
	v_sub_f32_e32 v52, v52, v94
	v_sub_f32_e32 v53, v53, v95
	v_sub_f32_e32 v54, v54, v96
	v_sub_f32_e32 v55, v55, v97
	v_mul_f32_e32 v40, v40, v56
	v_mul_f32_e32 v41, v41, v56
	v_mul_f32_e32 v42, v42, v56
	v_mul_f32_e32 v43, v43, v56
	v_mul_f32_e32 v44, v44, v56
	v_mul_f32_e32 v45, v45, v56
	v_mul_f32_e32 v46, v46, v56
	v_mul_f32_e32 v47, v47, v56
	v_fma_f32 v90, v48, v64, v90
	v_fma_f32 v91, v49, v65, v91
	v_fma_f32 v92, v50, v66, v92
	v_fma_f32 v93, v51, v67, v93
	v_fma_f32 v94, v52, v68, v94
	v_fma_f32 v95, v53, v69, v95
	v_fma_f32 v96, v54, v70, v96
	v_fma_f32 v97, v55, v71, v97
	v_mul_f32_e32 v90, v36, v90
	v_mul_f32_e32 v91, v36, v91
	v_mul_f32_e32 v92, v36, v92
	v_mul_f32_e32 v93, v36, v93
	v_mul_f32_e32 v94, v36, v94
	v_mul_f32_e32 v95, v36, v95
	v_mul_f32_e32 v96, v36, v96
	v_mul_f32_e32 v97, v36, v97
	v_fma_f32 v90, v40, v72, v90
	v_fma_f32 v91, v41, v73, v91
	v_fma_f32 v92, v42, v74, v92
	v_fma_f32 v93, v43, v75, v93
	v_fma_f32 v94, v44, v76, v94
	v_fma_f32 v95, v45, v77, v95
	v_fma_f32 v96, v46, v78, v96
	v_fma_f32 v97, v47, v79, v97
	v_lshlrev_b32_e32 v48, 16, v32
	v_and_b32_e32 v49, 0xffff0000, v32
	v_lshlrev_b32_e32 v50, 16, v33
	v_and_b32_e32 v51, 0xffff0000, v33
	v_lshlrev_b32_e32 v52, 16, v34
	v_and_b32_e32 v53, 0xffff0000, v34
	v_lshlrev_b32_e32 v54, 16, v35
	v_and_b32_e32 v55, 0xffff0000, v35
	v_mul_f32_e32 v90, v90, v48
	v_mul_f32_e32 v91, v91, v49
	v_mul_f32_e32 v92, v92, v50
	v_mul_f32_e32 v93, v93, v51
	v_mul_f32_e32 v94, v94, v52
	v_mul_f32_e32 v95, v95, v53
	v_mul_f32_e32 v96, v96, v54
	v_mul_f32_e32 v97, v97, v55
	v_cvt_pk_bf16_f32 v102, v90, v91
	v_cvt_pk_bf16_f32 v103, v92, v93
	v_cvt_pk_bf16_f32 v104, v94, v95
	v_cvt_pk_bf16_f32 v105, v96, v97
	s_add_u32 s28, s6, 0x7000000
	s_addc_u32 s29, s7, 0
	global_store_dwordx4 v61, v[102:105], s[28:29] offset:1024
	s_add_u32 s10, s6, 0x3d00000
	s_addc_u32 s11, s7, 0
	s_add_u32 s12, s6, 0x8e00000
	s_addc_u32 s13, s7, 0
	s_add_u32 s14, s6, 0xd900000
	s_addc_u32 s15, s7, 0
	s_add_u32 s18, s6, 0xfb50000
	s_addc_u32 s19, s7, 0
	global_load_dwordx4 v[20:23], v60, s[10:11]
	global_load_dwordx4 v[24:27], v88, s[12:13] offset:2048
	global_load_dwordx4 v[28:31], v89, s[12:13] offset:-1536
	global_load_dwordx4 v[32:35], v62, s[14:15] offset:2048
	global_load_dword v36, v63, s[18:19]
	s_waitcnt vmcnt(5)
	v_lshlrev_b32_e32 v40, 16, v0
	v_and_b32_e32 v41, 0xffff0000, v0
	v_lshlrev_b32_e32 v42, 16, v1
	v_and_b32_e32 v43, 0xffff0000, v1
	v_lshlrev_b32_e32 v44, 16, v2
	v_and_b32_e32 v45, 0xffff0000, v2
	v_lshlrev_b32_e32 v46, 16, v3
	v_and_b32_e32 v47, 0xffff0000, v3
	v_add_f32_e32 v56, 0, v40
	v_add_f32_e32 v56, v56, v41
	v_add_f32_e32 v56, v56, v42
	v_add_f32_e32 v56, v56, v43
	v_add_f32_e32 v56, v56, v44
	v_add_f32_e32 v56, v56, v45
	v_add_f32_e32 v56, v56, v46
	v_add_f32_e32 v56, v56, v47
	s_nop 1
	v_add_f32_dpp v56, v56, v56 quad_perm:[1,0,3,2] row_mask:0xf bank_mask:0xf
	s_nop 1
	v_add_f32_dpp v56, v56, v56 quad_perm:[2,3,0,1] row_mask:0xf bank_mask:0xf
	s_nop 1
	v_add_f32_dpp v56, v56, v56 row_half_mirror row_mask:0xf bank_mask:0xf
	v_mul_f32_e32 v57, 0x3c800000, v56
	v_sub_f32_e32 v40, v40, v57
	v_sub_f32_e32 v41, v41, v57
	v_sub_f32_e32 v42, v42, v57
	v_sub_f32_e32 v43, v43, v57
	v_sub_f32_e32 v44, v44, v57
	v_sub_f32_e32 v45, v45, v57
	v_sub_f32_e32 v46, v46, v57
	v_sub_f32_e32 v47, v47, v57
	v_mul_f32_e32 v56, v40, v40
	v_mul_f32_e32 v58, v41, v41
	v_add_f32_e32 v56, v56, v58
	v_mul_f32_e32 v58, v42, v42
	v_add_f32_e32 v56, v58, v56
	v_mul_f32_e32 v58, v43, v43
	v_add_f32_e32 v56, v58, v56
	v_mul_f32_e32 v58, v44, v44
	v_add_f32_e32 v56, v58, v56
	v_mul_f32_e32 v58, v45, v45
	v_add_f32_e32 v56, v58, v56
	v_mul_f32_e32 v58, v46, v46
	v_add_f32_e32 v56, v58, v56
	v_mul_f32_e32 v58, v47, v47
	v_add_f32_e32 v56, v58, v56
	s_nop 1
	v_add_f32_dpp v56, v56, v56 quad_perm:[1,0,3,2] row_mask:0xf bank_mask:0xf
	s_nop 1
	v_add_f32_dpp v56, v56, v56 quad_perm:[2,3,0,1] row_mask:0xf bank_mask:0xf
	s_nop 1
	v_add_f32_dpp v56, v56, v56 row_half_mirror row_mask:0xf bank_mask:0xf
	v_fmamk_f32 v56, v56, 0x3c800000, v87
	v_rsq_f32_e32 v56, v56
	v_cndmask_b32_e64 v8, 0, v8, s[26:27]
	v_cndmask_b32_e64 v9, 0, v9, s[26:27]
	v_cndmask_b32_e64 v10, 0, v10, s[26:27]
	v_cndmask_b32_e64 v11, 0, v11, s[26:27]
	v_lshlrev_b32_e32 v90, 16, v4
	v_and_b32_e32 v91, 0xffff0000, v4
	v_lshlrev_b32_e32 v48, 16, v8
	v_and_b32_e32 v49, 0xffff0000, v8
	v_lshlrev_b32_e32 v92, 16, v5
	v_and_b32_e32 v93, 0xffff0000, v5
	v_lshlrev_b32_e32 v50, 16, v9
	v_and_b32_e32 v51, 0xffff0000, v9
	v_lshlrev_b32_e32 v94, 16, v6
	v_and_b32_e32 v95, 0xffff0000, v6
	v_lshlrev_b32_e32 v52, 16, v10
	v_and_b32_e32 v53, 0xffff0000, v10
	v_lshlrev_b32_e32 v96, 16, v7
	v_and_b32_e32 v97, 0xffff0000, v7
	v_lshlrev_b32_e32 v54, 16, v11
	v_and_b32_e32 v55, 0xffff0000, v11
	v_sub_f32_e32 v48, v48, v90
	v_sub_f32_e32 v49, v49, v91
	v_sub_f32_e32 v50, v50, v92
	v_sub_f32_e32 v51, v51, v93
	v_sub_f32_e32 v52, v52, v94
	v_sub_f32_e32 v53, v53, v95
	v_sub_f32_e32 v54, v54, v96
	v_sub_f32_e32 v55, v55, v97
	v_mul_f32_e32 v40, v40, v56
	v_mul_f32_e32 v41, v41, v56
	v_mul_f32_e32 v42, v42, v56
	v_mul_f32_e32 v43, v43, v56
	v_mul_f32_e32 v44, v44, v56
	v_mul_f32_e32 v45, v45, v56
	v_mul_f32_e32 v46, v46, v56
	v_mul_f32_e32 v47, v47, v56
	v_fma_f32 v90, v48, v64, v90
	v_fma_f32 v91, v49, v65, v91
	v_fma_f32 v92, v50, v66, v92
	v_fma_f32 v93, v51, v67, v93
	v_fma_f32 v94, v52, v68, v94
	v_fma_f32 v95, v53, v69, v95
	v_fma_f32 v96, v54, v70, v96
	v_fma_f32 v97, v55, v71, v97
	v_mul_f32_e32 v90, v16, v90
	v_mul_f32_e32 v91, v16, v91
	v_mul_f32_e32 v92, v16, v92
	v_mul_f32_e32 v93, v16, v93
	v_mul_f32_e32 v94, v16, v94
	v_mul_f32_e32 v95, v16, v95
	v_mul_f32_e32 v96, v16, v96
	v_mul_f32_e32 v97, v16, v97
	v_fma_f32 v90, v40, v72, v90
	v_fma_f32 v91, v41, v73, v91
	v_fma_f32 v92, v42, v74, v92
	v_fma_f32 v93, v43, v75, v93
	v_fma_f32 v94, v44, v76, v94
	v_fma_f32 v95, v45, v77, v95
	v_fma_f32 v96, v46, v78, v96
	v_fma_f32 v97, v47, v79, v97
	v_lshlrev_b32_e32 v48, 16, v12
	v_and_b32_e32 v49, 0xffff0000, v12
	v_lshlrev_b32_e32 v50, 16, v13
	v_and_b32_e32 v51, 0xffff0000, v13
	v_lshlrev_b32_e32 v52, 16, v14
	v_and_b32_e32 v53, 0xffff0000, v14
	v_lshlrev_b32_e32 v54, 16, v15
	v_and_b32_e32 v55, 0xffff0000, v15
	v_mul_f32_e32 v90, v90, v48
	v_mul_f32_e32 v91, v91, v49
	v_mul_f32_e32 v92, v92, v50
	v_mul_f32_e32 v93, v93, v51
	v_mul_f32_e32 v94, v94, v52
	v_mul_f32_e32 v95, v95, v53
	v_mul_f32_e32 v96, v96, v54
	v_mul_f32_e32 v97, v97, v55
	v_cvt_pk_bf16_f32 v98, v90, v91
	v_cvt_pk_bf16_f32 v99, v92, v93
	v_cvt_pk_bf16_f32 v100, v94, v95
	v_cvt_pk_bf16_f32 v101, v96, v97
	s_add_u32 s28, s6, 0x7f00000
	s_addc_u32 s29, s7, 0
	global_store_dwordx4 v61, v[98:101], s[28:29] offset:1024
	s_add_u32 s10, s6, 0x3f00000
	s_addc_u32 s11, s7, 0
	s_add_u32 s12, s6, 0x9d00000
	s_addc_u32 s13, s7, 0
	s_add_u32 s14, s6, 0xdf00000
	s_addc_u32 s15, s7, 0
	s_add_u32 s18, s6, 0xfb60000
	s_addc_u32 s19, s7, 0
	global_load_dwordx4 v[0:3], v60, s[10:11]
	global_load_dwordx4 v[4:7], v88, s[12:13] offset:2048
	global_load_dwordx4 v[8:11], v89, s[12:13] offset:-1536
	global_load_dwordx4 v[12:15], v62, s[14:15] offset:2048
	global_load_dword v16, v63, s[18:19]
	s_waitcnt vmcnt(5)
	v_lshlrev_b32_e32 v40, 16, v20
	v_and_b32_e32 v41, 0xffff0000, v20
	v_lshlrev_b32_e32 v42, 16, v21
	v_and_b32_e32 v43, 0xffff0000, v21
	v_lshlrev_b32_e32 v44, 16, v22
	v_and_b32_e32 v45, 0xffff0000, v22
	v_lshlrev_b32_e32 v46, 16, v23
	v_and_b32_e32 v47, 0xffff0000, v23
	v_add_f32_e32 v56, 0, v40
	v_add_f32_e32 v56, v56, v41
	v_add_f32_e32 v56, v56, v42
	v_add_f32_e32 v56, v56, v43
	v_add_f32_e32 v56, v56, v44
	v_add_f32_e32 v56, v56, v45
	v_add_f32_e32 v56, v56, v46
	v_add_f32_e32 v56, v56, v47
	s_nop 1
	v_add_f32_dpp v56, v56, v56 quad_perm:[1,0,3,2] row_mask:0xf bank_mask:0xf
	s_nop 1
	v_add_f32_dpp v56, v56, v56 quad_perm:[2,3,0,1] row_mask:0xf bank_mask:0xf
	s_nop 1
	v_add_f32_dpp v56, v56, v56 row_half_mirror row_mask:0xf bank_mask:0xf
	v_mul_f32_e32 v57, 0x3c800000, v56
	v_sub_f32_e32 v40, v40, v57
	v_sub_f32_e32 v41, v41, v57
	v_sub_f32_e32 v42, v42, v57
	v_sub_f32_e32 v43, v43, v57
	v_sub_f32_e32 v44, v44, v57
	v_sub_f32_e32 v45, v45, v57
	v_sub_f32_e32 v46, v46, v57
	v_sub_f32_e32 v47, v47, v57
	v_mul_f32_e32 v56, v40, v40
	v_mul_f32_e32 v58, v41, v41
	v_add_f32_e32 v56, v56, v58
	v_mul_f32_e32 v58, v42, v42
	v_add_f32_e32 v56, v58, v56
	v_mul_f32_e32 v58, v43, v43
	v_add_f32_e32 v56, v58, v56
	v_mul_f32_e32 v58, v44, v44
	v_add_f32_e32 v56, v58, v56
	v_mul_f32_e32 v58, v45, v45
	v_add_f32_e32 v56, v58, v56
	v_mul_f32_e32 v58, v46, v46
	v_add_f32_e32 v56, v58, v56
	v_mul_f32_e32 v58, v47, v47
	v_add_f32_e32 v56, v58, v56
	s_nop 1
	v_add_f32_dpp v56, v56, v56 quad_perm:[1,0,3,2] row_mask:0xf bank_mask:0xf
	s_nop 1
	v_add_f32_dpp v56, v56, v56 quad_perm:[2,3,0,1] row_mask:0xf bank_mask:0xf
	s_nop 1
	v_add_f32_dpp v56, v56, v56 row_half_mirror row_mask:0xf bank_mask:0xf
	v_fmamk_f32 v56, v56, 0x3c800000, v87
	v_rsq_f32_e32 v56, v56
	v_cndmask_b32_e64 v28, 0, v28, s[26:27]
	v_cndmask_b32_e64 v29, 0, v29, s[26:27]
	v_cndmask_b32_e64 v30, 0, v30, s[26:27]
	v_cndmask_b32_e64 v31, 0, v31, s[26:27]
	v_lshlrev_b32_e32 v90, 16, v24
	v_and_b32_e32 v91, 0xffff0000, v24
	v_lshlrev_b32_e32 v48, 16, v28
	v_and_b32_e32 v49, 0xffff0000, v28
	v_lshlrev_b32_e32 v92, 16, v25
	v_and_b32_e32 v93, 0xffff0000, v25
	v_lshlrev_b32_e32 v50, 16, v29
	v_and_b32_e32 v51, 0xffff0000, v29
	v_lshlrev_b32_e32 v94, 16, v26
	v_and_b32_e32 v95, 0xffff0000, v26
	v_lshlrev_b32_e32 v52, 16, v30
	v_and_b32_e32 v53, 0xffff0000, v30
	v_lshlrev_b32_e32 v96, 16, v27
	v_and_b32_e32 v97, 0xffff0000, v27
	v_lshlrev_b32_e32 v54, 16, v31
	v_and_b32_e32 v55, 0xffff0000, v31
	v_sub_f32_e32 v48, v48, v90
	v_sub_f32_e32 v49, v49, v91
	v_sub_f32_e32 v50, v50, v92
	v_sub_f32_e32 v51, v51, v93
	v_sub_f32_e32 v52, v52, v94
	v_sub_f32_e32 v53, v53, v95
	v_sub_f32_e32 v54, v54, v96
	v_sub_f32_e32 v55, v55, v97
	v_mul_f32_e32 v40, v40, v56
	v_mul_f32_e32 v41, v41, v56
	v_mul_f32_e32 v42, v42, v56
	v_mul_f32_e32 v43, v43, v56
	v_mul_f32_e32 v44, v44, v56
	v_mul_f32_e32 v45, v45, v56
	v_mul_f32_e32 v46, v46, v56
	v_mul_f32_e32 v47, v47, v56
	v_fma_f32 v90, v48, v64, v90
	v_fma_f32 v91, v49, v65, v91
	v_fma_f32 v92, v50, v66, v92
	v_fma_f32 v93, v51, v67, v93
	v_fma_f32 v94, v52, v68, v94
	v_fma_f32 v95, v53, v69, v95
	v_fma_f32 v96, v54, v70, v96
	v_fma_f32 v97, v55, v71, v97
	v_mul_f32_e32 v90, v36, v90
	v_mul_f32_e32 v91, v36, v91
	v_mul_f32_e32 v92, v36, v92
	v_mul_f32_e32 v93, v36, v93
	v_mul_f32_e32 v94, v36, v94
	v_mul_f32_e32 v95, v36, v95
	v_mul_f32_e32 v96, v36, v96
	v_mul_f32_e32 v97, v36, v97
	v_fma_f32 v90, v40, v72, v90
	v_fma_f32 v91, v41, v73, v91
	v_fma_f32 v92, v42, v74, v92
	v_fma_f32 v93, v43, v75, v93
	v_fma_f32 v94, v44, v76, v94
	v_fma_f32 v95, v45, v77, v95
	v_fma_f32 v96, v46, v78, v96
	v_fma_f32 v97, v47, v79, v97
	v_lshlrev_b32_e32 v48, 16, v32
	v_and_b32_e32 v49, 0xffff0000, v32
	v_lshlrev_b32_e32 v50, 16, v33
	v_and_b32_e32 v51, 0xffff0000, v33
	v_lshlrev_b32_e32 v52, 16, v34
	v_and_b32_e32 v53, 0xffff0000, v34
	v_lshlrev_b32_e32 v54, 16, v35
	v_and_b32_e32 v55, 0xffff0000, v35
	v_mul_f32_e32 v90, v90, v48
	v_mul_f32_e32 v91, v91, v49
	v_mul_f32_e32 v92, v92, v50
	v_mul_f32_e32 v93, v93, v51
	v_mul_f32_e32 v94, v94, v52
	v_mul_f32_e32 v95, v95, v53
	v_mul_f32_e32 v96, v96, v54
	v_mul_f32_e32 v97, v97, v55
	v_cvt_pk_bf16_f32 v102, v90, v91
	v_cvt_pk_bf16_f32 v103, v92, v93
	v_cvt_pk_bf16_f32 v104, v94, v95
	v_cvt_pk_bf16_f32 v105, v96, v97
	s_add_u32 s28, s6, 0x8e00000
	s_addc_u32 s29, s7, 0
	global_store_dwordx4 v61, v[102:105], s[28:29] offset:1024
	s_add_u32 s10, s6, 0x4100000
	s_addc_u32 s11, s7, 0
	s_add_u32 s12, s6, 0xac00000
	s_addc_u32 s13, s7, 0
	s_add_u32 s14, s6, 0xe500000
	s_addc_u32 s15, s7, 0
	s_add_u32 s18, s6, 0xfb70000
	s_addc_u32 s19, s7, 0
	global_load_dwordx4 v[20:23], v60, s[10:11]
	global_load_dwordx4 v[24:27], v88, s[12:13] offset:2048
	global_load_dwordx4 v[28:31], v89, s[12:13] offset:-1536
	global_load_dwordx4 v[32:35], v62, s[14:15] offset:2048
	global_load_dword v36, v63, s[18:19]
	s_waitcnt vmcnt(5)
	v_lshlrev_b32_e32 v40, 16, v0
	v_and_b32_e32 v41, 0xffff0000, v0
	v_lshlrev_b32_e32 v42, 16, v1
	v_and_b32_e32 v43, 0xffff0000, v1
	v_lshlrev_b32_e32 v44, 16, v2
	v_and_b32_e32 v45, 0xffff0000, v2
	v_lshlrev_b32_e32 v46, 16, v3
	v_and_b32_e32 v47, 0xffff0000, v3
	v_add_f32_e32 v56, 0, v40
	v_add_f32_e32 v56, v56, v41
	v_add_f32_e32 v56, v56, v42
	v_add_f32_e32 v56, v56, v43
	v_add_f32_e32 v56, v56, v44
	v_add_f32_e32 v56, v56, v45
	v_add_f32_e32 v56, v56, v46
	v_add_f32_e32 v56, v56, v47
	s_nop 1
	v_add_f32_dpp v56, v56, v56 quad_perm:[1,0,3,2] row_mask:0xf bank_mask:0xf
	s_nop 1
	v_add_f32_dpp v56, v56, v56 quad_perm:[2,3,0,1] row_mask:0xf bank_mask:0xf
	s_nop 1
	v_add_f32_dpp v56, v56, v56 row_half_mirror row_mask:0xf bank_mask:0xf
	v_mul_f32_e32 v57, 0x3c800000, v56
	v_sub_f32_e32 v40, v40, v57
	v_sub_f32_e32 v41, v41, v57
	v_sub_f32_e32 v42, v42, v57
	v_sub_f32_e32 v43, v43, v57
	v_sub_f32_e32 v44, v44, v57
	v_sub_f32_e32 v45, v45, v57
	v_sub_f32_e32 v46, v46, v57
	v_sub_f32_e32 v47, v47, v57
	v_mul_f32_e32 v56, v40, v40
	v_mul_f32_e32 v58, v41, v41
	v_add_f32_e32 v56, v56, v58
	v_mul_f32_e32 v58, v42, v42
	v_add_f32_e32 v56, v58, v56
	v_mul_f32_e32 v58, v43, v43
	v_add_f32_e32 v56, v58, v56
	v_mul_f32_e32 v58, v44, v44
	v_add_f32_e32 v56, v58, v56
	v_mul_f32_e32 v58, v45, v45
	v_add_f32_e32 v56, v58, v56
	v_mul_f32_e32 v58, v46, v46
	v_add_f32_e32 v56, v58, v56
	v_mul_f32_e32 v58, v47, v47
	v_add_f32_e32 v56, v58, v56
	s_nop 1
	v_add_f32_dpp v56, v56, v56 quad_perm:[1,0,3,2] row_mask:0xf bank_mask:0xf
	s_nop 1
	v_add_f32_dpp v56, v56, v56 quad_perm:[2,3,0,1] row_mask:0xf bank_mask:0xf
	s_nop 1
	v_add_f32_dpp v56, v56, v56 row_half_mirror row_mask:0xf bank_mask:0xf
	v_fmamk_f32 v56, v56, 0x3c800000, v87
	v_rsq_f32_e32 v56, v56
	v_cndmask_b32_e64 v8, 0, v8, s[26:27]
	v_cndmask_b32_e64 v9, 0, v9, s[26:27]
	v_cndmask_b32_e64 v10, 0, v10, s[26:27]
	v_cndmask_b32_e64 v11, 0, v11, s[26:27]
	v_lshlrev_b32_e32 v90, 16, v4
	v_and_b32_e32 v91, 0xffff0000, v4
	v_lshlrev_b32_e32 v48, 16, v8
	v_and_b32_e32 v49, 0xffff0000, v8
	v_lshlrev_b32_e32 v92, 16, v5
	v_and_b32_e32 v93, 0xffff0000, v5
	v_lshlrev_b32_e32 v50, 16, v9
	v_and_b32_e32 v51, 0xffff0000, v9
	v_lshlrev_b32_e32 v94, 16, v6
	v_and_b32_e32 v95, 0xffff0000, v6
	v_lshlrev_b32_e32 v52, 16, v10
	v_and_b32_e32 v53, 0xffff0000, v10
	v_lshlrev_b32_e32 v96, 16, v7
	v_and_b32_e32 v97, 0xffff0000, v7
	v_lshlrev_b32_e32 v54, 16, v11
	v_and_b32_e32 v55, 0xffff0000, v11
	v_sub_f32_e32 v48, v48, v90
	v_sub_f32_e32 v49, v49, v91
	v_sub_f32_e32 v50, v50, v92
	v_sub_f32_e32 v51, v51, v93
	v_sub_f32_e32 v52, v52, v94
	v_sub_f32_e32 v53, v53, v95
	v_sub_f32_e32 v54, v54, v96
	v_sub_f32_e32 v55, v55, v97
	v_mul_f32_e32 v40, v40, v56
	v_mul_f32_e32 v41, v41, v56
	v_mul_f32_e32 v42, v42, v56
	v_mul_f32_e32 v43, v43, v56
	v_mul_f32_e32 v44, v44, v56
	v_mul_f32_e32 v45, v45, v56
	v_mul_f32_e32 v46, v46, v56
	v_mul_f32_e32 v47, v47, v56
	v_fma_f32 v90, v48, v64, v90
	v_fma_f32 v91, v49, v65, v91
	v_fma_f32 v92, v50, v66, v92
	v_fma_f32 v93, v51, v67, v93
	v_fma_f32 v94, v52, v68, v94
	v_fma_f32 v95, v53, v69, v95
	v_fma_f32 v96, v54, v70, v96
	v_fma_f32 v97, v55, v71, v97
	v_mul_f32_e32 v90, v16, v90
	v_mul_f32_e32 v91, v16, v91
	v_mul_f32_e32 v92, v16, v92
	v_mul_f32_e32 v93, v16, v93
	v_mul_f32_e32 v94, v16, v94
	v_mul_f32_e32 v95, v16, v95
	v_mul_f32_e32 v96, v16, v96
	v_mul_f32_e32 v97, v16, v97
	v_fma_f32 v90, v40, v72, v90
	v_fma_f32 v91, v41, v73, v91
	v_fma_f32 v92, v42, v74, v92
	v_fma_f32 v93, v43, v75, v93
	v_fma_f32 v94, v44, v76, v94
	v_fma_f32 v95, v45, v77, v95
	v_fma_f32 v96, v46, v78, v96
	v_fma_f32 v97, v47, v79, v97
	v_lshlrev_b32_e32 v48, 16, v12
	v_and_b32_e32 v49, 0xffff0000, v12
	v_lshlrev_b32_e32 v50, 16, v13
	v_and_b32_e32 v51, 0xffff0000, v13
	v_lshlrev_b32_e32 v52, 16, v14
	v_and_b32_e32 v53, 0xffff0000, v14
	v_lshlrev_b32_e32 v54, 16, v15
	v_and_b32_e32 v55, 0xffff0000, v15
	v_mul_f32_e32 v90, v90, v48
	v_mul_f32_e32 v91, v91, v49
	v_mul_f32_e32 v92, v92, v50
	v_mul_f32_e32 v93, v93, v51
	v_mul_f32_e32 v94, v94, v52
	v_mul_f32_e32 v95, v95, v53
	v_mul_f32_e32 v96, v96, v54
	v_mul_f32_e32 v97, v97, v55
	v_cvt_pk_bf16_f32 v98, v90, v91
	v_cvt_pk_bf16_f32 v99, v92, v93
	v_cvt_pk_bf16_f32 v100, v94, v95
	v_cvt_pk_bf16_f32 v101, v96, v97
	s_add_u32 s28, s6, 0x9d00000
	s_addc_u32 s29, s7, 0
	global_store_dwordx4 v61, v[98:101], s[28:29] offset:1024
	s_waitcnt vmcnt(0)
	v_lshlrev_b32_e32 v40, 16, v20
	v_and_b32_e32 v41, 0xffff0000, v20
	v_lshlrev_b32_e32 v42, 16, v21
	v_and_b32_e32 v43, 0xffff0000, v21
	v_lshlrev_b32_e32 v44, 16, v22
	v_and_b32_e32 v45, 0xffff0000, v22
	v_lshlrev_b32_e32 v46, 16, v23
	v_and_b32_e32 v47, 0xffff0000, v23
	v_add_f32_e32 v56, 0, v40
	v_add_f32_e32 v56, v56, v41
	v_add_f32_e32 v56, v56, v42
	v_add_f32_e32 v56, v56, v43
	v_add_f32_e32 v56, v56, v44
	v_add_f32_e32 v56, v56, v45
	v_add_f32_e32 v56, v56, v46
	v_add_f32_e32 v56, v56, v47
	s_nop 1
	v_add_f32_dpp v56, v56, v56 quad_perm:[1,0,3,2] row_mask:0xf bank_mask:0xf
	s_nop 1
	v_add_f32_dpp v56, v56, v56 quad_perm:[2,3,0,1] row_mask:0xf bank_mask:0xf
	s_nop 1
	v_add_f32_dpp v56, v56, v56 row_half_mirror row_mask:0xf bank_mask:0xf
	v_mul_f32_e32 v57, 0x3c800000, v56
	v_sub_f32_e32 v40, v40, v57
	v_sub_f32_e32 v41, v41, v57
	v_sub_f32_e32 v42, v42, v57
	v_sub_f32_e32 v43, v43, v57
	v_sub_f32_e32 v44, v44, v57
	v_sub_f32_e32 v45, v45, v57
	v_sub_f32_e32 v46, v46, v57
	v_sub_f32_e32 v47, v47, v57
	v_mul_f32_e32 v56, v40, v40
	v_mul_f32_e32 v58, v41, v41
	v_add_f32_e32 v56, v56, v58
	v_mul_f32_e32 v58, v42, v42
	v_add_f32_e32 v56, v58, v56
	v_mul_f32_e32 v58, v43, v43
	v_add_f32_e32 v56, v58, v56
	v_mul_f32_e32 v58, v44, v44
	v_add_f32_e32 v56, v58, v56
	v_mul_f32_e32 v58, v45, v45
	v_add_f32_e32 v56, v58, v56
	v_mul_f32_e32 v58, v46, v46
	v_add_f32_e32 v56, v58, v56
	v_mul_f32_e32 v58, v47, v47
	v_add_f32_e32 v56, v58, v56
	s_nop 1
	v_add_f32_dpp v56, v56, v56 quad_perm:[1,0,3,2] row_mask:0xf bank_mask:0xf
	s_nop 1
	v_add_f32_dpp v56, v56, v56 quad_perm:[2,3,0,1] row_mask:0xf bank_mask:0xf
	s_nop 1
	v_add_f32_dpp v56, v56, v56 row_half_mirror row_mask:0xf bank_mask:0xf
	v_fmamk_f32 v56, v56, 0x3c800000, v87
	v_rsq_f32_e32 v56, v56
	v_cndmask_b32_e64 v28, 0, v28, s[26:27]
	v_cndmask_b32_e64 v29, 0, v29, s[26:27]
	v_cndmask_b32_e64 v30, 0, v30, s[26:27]
	v_cndmask_b32_e64 v31, 0, v31, s[26:27]
	v_lshlrev_b32_e32 v90, 16, v24
	v_and_b32_e32 v91, 0xffff0000, v24
	v_lshlrev_b32_e32 v48, 16, v28
	v_and_b32_e32 v49, 0xffff0000, v28
	v_lshlrev_b32_e32 v92, 16, v25
	v_and_b32_e32 v93, 0xffff0000, v25
	v_lshlrev_b32_e32 v50, 16, v29
	v_and_b32_e32 v51, 0xffff0000, v29
	v_lshlrev_b32_e32 v94, 16, v26
	v_and_b32_e32 v95, 0xffff0000, v26
	v_lshlrev_b32_e32 v52, 16, v30
	v_and_b32_e32 v53, 0xffff0000, v30
	v_lshlrev_b32_e32 v96, 16, v27
	v_and_b32_e32 v97, 0xffff0000, v27
	v_lshlrev_b32_e32 v54, 16, v31
	v_and_b32_e32 v55, 0xffff0000, v31
	v_sub_f32_e32 v48, v48, v90
	v_sub_f32_e32 v49, v49, v91
	v_sub_f32_e32 v50, v50, v92
	v_sub_f32_e32 v51, v51, v93
	v_sub_f32_e32 v52, v52, v94
	v_sub_f32_e32 v53, v53, v95
	v_sub_f32_e32 v54, v54, v96
	v_sub_f32_e32 v55, v55, v97
	v_mul_f32_e32 v40, v40, v56
	v_mul_f32_e32 v41, v41, v56
	v_mul_f32_e32 v42, v42, v56
	v_mul_f32_e32 v43, v43, v56
	v_mul_f32_e32 v44, v44, v56
	v_mul_f32_e32 v45, v45, v56
	v_mul_f32_e32 v46, v46, v56
	v_mul_f32_e32 v47, v47, v56
	v_fma_f32 v90, v48, v64, v90
	v_fma_f32 v91, v49, v65, v91
	v_fma_f32 v92, v50, v66, v92
	v_fma_f32 v93, v51, v67, v93
	v_fma_f32 v94, v52, v68, v94
	v_fma_f32 v95, v53, v69, v95
	v_fma_f32 v96, v54, v70, v96
	v_fma_f32 v97, v55, v71, v97
	v_mul_f32_e32 v90, v36, v90
	v_mul_f32_e32 v91, v36, v91
	v_mul_f32_e32 v92, v36, v92
	v_mul_f32_e32 v93, v36, v93
	v_mul_f32_e32 v94, v36, v94
	v_mul_f32_e32 v95, v36, v95
	v_mul_f32_e32 v96, v36, v96
	v_mul_f32_e32 v97, v36, v97
	v_fma_f32 v90, v40, v72, v90
	v_fma_f32 v91, v41, v73, v91
	v_fma_f32 v92, v42, v74, v92
	v_fma_f32 v93, v43, v75, v93
	v_fma_f32 v94, v44, v76, v94
	v_fma_f32 v95, v45, v77, v95
	v_fma_f32 v96, v46, v78, v96
	v_fma_f32 v97, v47, v79, v97
	v_lshlrev_b32_e32 v48, 16, v32
	v_and_b32_e32 v49, 0xffff0000, v32
	v_lshlrev_b32_e32 v50, 16, v33
	v_and_b32_e32 v51, 0xffff0000, v33
	v_lshlrev_b32_e32 v52, 16, v34
	v_and_b32_e32 v53, 0xffff0000, v34
	v_lshlrev_b32_e32 v54, 16, v35
	v_and_b32_e32 v55, 0xffff0000, v35
	v_mul_f32_e32 v90, v90, v48
	v_mul_f32_e32 v91, v91, v49
	v_mul_f32_e32 v92, v92, v50
	v_mul_f32_e32 v93, v93, v51
	v_mul_f32_e32 v94, v94, v52
	v_mul_f32_e32 v95, v95, v53
	v_mul_f32_e32 v96, v96, v54
	v_mul_f32_e32 v97, v97, v55
	v_cvt_pk_bf16_f32 v102, v90, v91
	v_cvt_pk_bf16_f32 v103, v92, v93
	v_cvt_pk_bf16_f32 v104, v94, v95
	v_cvt_pk_bf16_f32 v105, v96, v97
	s_add_u32 s28, s6, 0xac00000
	s_addc_u32 s29, s7, 0
	global_store_dwordx4 v61, v[102:105], s[28:29] offset:1024
	s_mov_b64 s[4:5], 0
